# bundle: wkv output-block LDS reads hoisted + resident-parameter copies forward-substituted into their consumers + scan staging waits only for loads on the chain wave + phase8 row loop software-pipelin
# speedup vs baseline: 1.0071x; 1.0071x over previous
.Lres_skip_7:
	s_waitcnt vmcnt(8)
	s_lshl_b32 s4, s8, 6
	v_ashrrev_i32_e32 v141, 3, v137
	v_add_u32_e32 v88, s4, v141
	v_lshlrev_b32_e32 v66, 16, v28
	v_cmp_lt_i32_e32 vcc, 0, v88
	v_lshlrev_b32_e32 v42, 16, v24
	v_and_b32_e32 v67, 0xffff0000, v28
	v_cndmask_b32_e32 v66, 0, v66, vcc
	v_and_b32_e32 v72, 0xffff0000, v24
	v_and_b32_e32 v80, 0xffff0000, v31
	v_and_b32_e32 v81, 0xffff0000, v36
	v_sub_f32_e32 v88, v66, v42
	v_cndmask_b32_e32 v89, 0, v67, vcc
	v_and_b32_e32 v79, 0xffff0000, v27
	v_cndmask_b32_e32 v80, 0, v80, vcc
	v_cndmask_b32_e32 v67, 0, v81, vcc
	v_sub_f32_e32 v81, v89, v72
	v_sub_f32_e32 v80, v80, v79
	v_lshlrev_b32_e32 v78, 16, v31
	v_lshlrev_b32_e32 v68, 16, v29
	v_lshlrev_b32_e32 v77, 16, v27
	v_cndmask_b32_e32 v78, 0, v78, vcc
	v_lshlrev_b32_e32 v73, 16, v25
	v_and_b32_e32 v69, 0xffff0000, v29
	v_lshlrev_b32_e32 v82, 16, v36
	v_cndmask_b32_e32 v90, 0, v68, vcc
	v_sub_f32_e32 v78, v78, v77
	v_and_b32_e32 v74, 0xffff0000, v25
	v_and_b32_e32 v83, 0xffff0000, v37
	v_and_b32_e32 v87, 0xffff0000, v39
	v_cndmask_b32_e32 v91, 0, v69, vcc
	v_cndmask_b32_e32 v66, 0, v82, vcc
	v_sub_f32_e32 v82, v90, v73
	v_and_b32_e32 v65, 0xffff0000, v35
	v_lshlrev_b32_e32 v64, 16, v35
	v_cndmask_b32_e32 v69, 0, v83, vcc
	v_sub_f32_e32 v83, v91, v74
	v_lshlrev_b32_e32 v70, 16, v30
	v_lshlrev_b32_e32 v75, 16, v26
	v_and_b32_e32 v71, 0xffff0000, v30
	v_lshlrev_b32_e32 v84, 16, v37
	v_cndmask_b32_e32 v92, 0, v70, vcc
	v_and_b32_e32 v76, 0xffff0000, v26
	v_and_b32_e32 v85, 0xffff0000, v38
	v_cndmask_b32_e32 v93, 0, v71, vcc
	v_cndmask_b32_e32 v68, 0, v84, vcc
	v_sub_f32_e32 v84, v92, v75
	v_cndmask_b32_e32 v71, 0, v85, vcc
	v_sub_f32_e32 v85, v93, v76
	v_and_b32_e32 v41, 0xffff0000, v32
	v_lshlrev_b32_e32 v40, 16, v32
	v_pk_add_f32 v[66:67], v[66:67], v[40:41] neg_lo:[0,1] neg_hi:[0,1]
	v_lshlrev_b32_e32 v86, 16, v38
	v_and_b32_e32 v61, 0xffff0000, v33
	v_lshlrev_b32_e32 v60, 16, v33
	v_and_b32_e32 v63, 0xffff0000, v34
	v_lshlrev_b32_e32 v62, 16, v34
	v_cndmask_b32_e32 v70, 0, v86, vcc
	v_pk_add_f32 v[68:69], v[68:69], v[60:61] neg_lo:[0,1] neg_hi:[0,1]
	v_pk_add_f32 v[70:71], v[70:71], v[62:63] neg_lo:[0,1] neg_hi:[0,1]
	s_movk_i32 s0, 0x100
	s_and_b32 s5, s2, 7
	v_cmp_gt_u32_e64 s[0:1], s0, v137
	s_lshl_b32 s9, s5, 6
	s_lshl_b32 s12, s5, 13
	v_and_b32_e32 v135, 15, v137
	v_or_b32_e32 v146, s9, v142
	v_readlane_b32 s36, v241, 33
	v_lshlrev_b32_e32 v147, 2, v146
	v_readlane_b32 s40, v241, 37
	v_readlane_b32 s41, v241, 38
	v_ashrrev_i32_e32 v138, 6, v137
	v_lshrrev_b32_e32 v96, 8, v137
	v_bfe_u32 v139, v137, 4, 2
	v_lshlrev_b32_e32 v145, 2, v139
	v_readlane_b32 s42, v241, 39
	s_waitcnt vmcnt(8)
	v_fmac_f32_e32 v42, v88, v156
	v_fmac_f32_e32 v72, v81, v157
	v_mul_f32_e32 v42, 0x4038aa3b, v42
	s_waitcnt vmcnt(8)
	v_fmac_f32_e32 v79, v80, v163
	v_exp_f32_e32 v42, v42
	v_mul_f32_e32 v51, 0x4038aa3b, v72
	v_exp_f32_e32 v53, v51
	v_fmac_f32_e32 v77, v78, v162
	v_lshlrev_b32_e32 v50, 16, v39
	v_add_f32_e32 v42, 1.0, v42
	v_fmac_f32_e32 v73, v82, v158
	v_cndmask_b32_e32 v51, 0, v87, vcc
	v_rcp_f32_e32 v52, v42
	v_add_f32_e32 v42, 1.0, v53
	v_cndmask_b32_e32 v50, 0, v50, vcc
	v_fmac_f32_e32 v74, v83, v159
	v_rcp_f32_e32 v53, v42
	v_pk_add_f32 v[50:51], v[50:51], v[64:65] neg_lo:[0,1] neg_hi:[0,1]
	v_mul_f32_e32 v42, 0x4038aa3b, v73
	s_waitcnt vmcnt(8)
	v_mov_b32_e32 v44, v176
	v_mov_b32_e32 v45, v177
	v_pk_fma_f32 v[54:55], v[50:51], v[178:179], v[64:65]
	v_exp_f32_e32 v42, v42
	v_mul_f32_e32 v50, 0x4038aa3b, v74
	v_exp_f32_e32 v51, v50
	v_pk_fma_f32 v[46:47], v[52:53], 2.0, 1.0 op_sel_hi:[1,0,0] neg_lo:[1,0,0] neg_hi:[1,0,0]
	v_add_f32_e32 v42, 1.0, v42
	v_fmac_f32_e32 v75, v84, v160
	v_cvt_pk_bf16_f32 v50, v46, v47
	v_rcp_f32_e32 v46, v42
	v_add_f32_e32 v42, 1.0, v51
	v_fmac_f32_e32 v76, v85, v161
	v_rcp_f32_e32 v47, v42
	v_mul_f32_e32 v42, 0x4038aa3b, v75
	v_exp_f32_e32 v42, v42
	v_mul_f32_e32 v51, 0x4038aa3b, v76
	v_exp_f32_e32 v51, v51
	v_mul_f32_e32 v53, 0x4038aa3b, v79
	v_add_f32_e32 v42, 1.0, v42
	v_rcp_f32_e32 v52, v42
	v_add_f32_e32 v42, 1.0, v51
	v_mul_f32_e32 v51, 0x4038aa3b, v77
	v_exp_f32_e32 v51, v51
	v_pk_fma_f32 v[40:41], v[66:67], v[168:169], v[40:41]
	v_exp_f32_e32 v57, v53
	v_rcp_f32_e32 v53, v42
	v_add_f32_e32 v42, 1.0, v51
	v_rcp_f32_e32 v56, v42
	v_add_f32_e32 v42, 1.0, v57
	v_rcp_f32_e32 v57, v42
	v_pk_fma_f32 v[46:47], v[46:47], 2.0, 1.0 op_sel_hi:[1,0,0] neg_lo:[1,0,0] neg_hi:[1,0,0]
	v_pk_fma_f32 v[48:49], v[68:69], v[170:171], v[60:61]
	v_cvt_pk_bf16_f32 v51, v46, v47
	v_pk_fma_f32 v[46:47], v[52:53], 2.0, 1.0 op_sel_hi:[1,0,0] neg_lo:[1,0,0] neg_hi:[1,0,0]
	v_pk_fma_f32 v[44:45], v[70:71], v[44:45], v[62:63]
	v_cvt_pk_bf16_f32 v52, v46, v47
	v_pk_fma_f32 v[46:47], v[56:57], 2.0, 1.0 op_sel_hi:[1,0,0] neg_lo:[1,0,0] neg_hi:[1,0,0]
	v_and_b32_e32 v42, 48, v137
	v_cvt_pk_bf16_f32 v53, v46, v47
	v_cvt_pk_bf16_f32 v46, v40, v41
	v_mul_lo_u32 v40, v141, s96
	v_lshlrev_b32_e32 v41, 1, v142
	v_cvt_pk_bf16_f32 v47, v48, v49
	v_cvt_pk_bf16_f32 v48, v44, v45
	v_cvt_pk_bf16_f32 v49, v54, v55
	v_add3_u32 v143, 0, v40, v41
	v_add3_u32 v40, s97, v40, v41
	ds_write_b128 v40, v[46:49]
	v_cndmask_b32_e64 v41, v123, v124, s[0:1]
	v_cndmask_b32_e64 v40, v125, v126, s[0:1]
	v_lshl_add_u64 v[40:41], v[40:41], 0, s[12:13]
	ds_write_b128 v143, v[50:53] offset:64512
	v_lshl_add_u64 v[40:41], v[40:41], 0, v[42:43]
	v_lshlrev_b32_e32 v44, 7, v135
	v_mov_b32_e32 v45, v43
	v_lshl_add_u64 v[40:41], v[40:41], 0, v[44:45]
	global_load_dwordx4 v[44:47], v147, s[30:31] offset:16
	global_load_dwordx4 v[52:55], v147, s[30:31]
	global_load_dwordx4 v[48:51], v147, s[40:41] offset:16
	global_load_dwordx4 v[64:67], v147, s[40:41]
	global_load_dwordx4 v[72:75], v147, s[40:41] offset:2064
	global_load_dwordx4 v[68:71], v147, s[40:41] offset:2048
	s_waitcnt lgkmcnt(0)
	s_barrier
	s_cmp_lg_u32 s101, 0
	s_cbranch_scc1 .Lres_skip_197
	global_load_dwordx4 v[180:183], v[40:41], off
	global_load_dwordx4 v[184:187], v[40:41], off offset:64
	global_load_dwordx4 v[188:191], v[40:41], off offset:2048
	global_load_dwordx4 v[192:195], v[40:41], off offset:2112
	s_mov_b32 s98, 0x1000
	s_mov_b32 s99, 0
	v_lshl_add_u64 v[242:243], v[40:41], 0, s[98:99]
	global_load_dwordx4 v[196:199], v[242:243], off
	global_load_dwordx4 v[200:203], v[242:243], off offset:64
	global_load_dwordx4 v[204:207], v[242:243], off offset:2048
	global_load_dwordx4 v[208:211], v[242:243], off offset:2112
.Lres_skip_197:
	v_cndmask_b32_e64 v60, v121, v122, s[0:1]
	s_movk_i32 s0, 0x1000
	v_add_co_u32_e64 v40, s[0:1], s0, v40
	v_lshlrev_b32_e32 v56, 4, v138
	s_nop 0
	v_addc_co_u32_e64 v41, s[0:1], 0, v41, s[0:1]
	v_and_b32_e32 v108, 48, v56
	v_or_b32_e32 v40, v108, v135
	v_mul_u32_u24_e32 v40, 0x90, v40
	v_add3_u32 v109, v60, v40, v42
	ds_read_b128 v[60:63], v109
	s_movk_i32 s1, 0x4100
	v_mad_i32_i24 v40, v96, s1, v127
	ds_read_b128 v[96:99], v109 offset:64
	v_or_b32_e32 v41, v108, v145
	v_lshlrev_b32_e32 v108, 2, v135
	v_mul_u32_u24_e32 v41, 0x104, v41
	v_add3_u32 v108, v40, v108, v41
	v_and_b32_e32 v41, 0xffff0000, v16
	v_lshlrev_b32_e32 v40, 16, v16
	v_readlane_b32 s43, v241, 40
	v_readlane_b32 s46, v241, 43
	v_readlane_b32 s47, v241, 44
	v_readlane_b32 s50, v241, 47
	v_readlane_b32 s51, v241, 48
	v_readlane_b32 s72, v241, 49
	v_readlane_b32 s73, v241, 50
	s_movk_i32 s1, 0x104
	v_mul_lo_u32 v148, v141, s1
	v_readlane_b32 s1, v241, 8
	s_waitcnt vmcnt(0) lgkmcnt(1)
	s_nop 1
	v_mfma_f32_16x16x32_bf16 v[60:63], v[60:63], v[180:183], 0
	v_and_b32_e32 v77, 0xffff0000, v20
	v_add3_u32 v76, s1, v148, v144
	s_lshl_b32 s0, s2, 3
	s_waitcnt vmcnt(0) lgkmcnt(0)
	s_nop 1
	v_mfma_f32_16x16x32_bf16 v[60:63], v[96:99], v[184:187], v[60:63]
	s_nop 7
	ds_write_b32 v108, v60
	ds_write_b32 v108, v61 offset:260
	ds_write_b32 v108, v62 offset:520
	ds_write_b32 v108, v63 offset:780
	ds_read_b128 v[60:63], v109
	ds_read_b128 v[78:81], v109 offset:64
	s_waitcnt vmcnt(0) lgkmcnt(1)
	s_nop 1
	v_mfma_f32_16x16x32_bf16 v[60:63], v[60:63], v[188:191], 0
	v_lshlrev_b32_e32 v84, 16, v20
	v_cndmask_b32_e32 v85, 0, v77, vcc
	v_cndmask_b32_e32 v84, 0, v84, vcc
	s_waitcnt vmcnt(0) lgkmcnt(0)
	s_nop 1
	v_mfma_f32_16x16x32_bf16 v[60:63], v[78:81], v[192:195], v[60:63]
	s_nop 7
	ds_write_b32 v108, v60 offset:64
	ds_write_b32 v108, v61 offset:324
	ds_write_b32 v108, v62 offset:584
	ds_write_b32 v108, v63 offset:844
	ds_read_b128 v[60:63], v109
	v_pk_add_f32 v[78:79], v[84:85], v[40:41] neg_lo:[0,1] neg_hi:[0,1]
	v_and_b32_e32 v77, 0xffff0000, v22
	v_pk_fma_f32 v[40:41], v[78:79], v[52:53], v[40:41]
	ds_read_b128 v[78:81], v109 offset:64
	s_waitcnt vmcnt(0) lgkmcnt(1)
	s_nop 1
	v_mfma_f32_16x16x32_bf16 v[60:63], v[60:63], v[196:199], 0
	v_lshlrev_b32_e32 v84, 16, v22
	v_and_b32_e32 v53, 0xffff0000, v18
	v_lshlrev_b32_e32 v52, 16, v18
	s_waitcnt vmcnt(0) lgkmcnt(0)
	s_nop 1
	v_mfma_f32_16x16x32_bf16 v[60:63], v[78:81], v[200:203], v[60:63]
	s_nop 7
	ds_write_b32 v108, v60 offset:128
	ds_write_b32 v108, v61 offset:388
	ds_write_b32 v108, v62 offset:648
	ds_write_b32 v108, v63 offset:908
	ds_read_b128 v[60:63], v109
	ds_read_b128 v[78:81], v109 offset:64
	v_cndmask_b32_e32 v85, 0, v77, vcc
	v_cndmask_b32_e32 v84, 0, v84, vcc
	v_pk_add_f32 v[84:85], v[84:85], v[52:53] neg_lo:[0,1] neg_hi:[0,1]
	s_waitcnt vmcnt(0) lgkmcnt(1)
	s_nop 1
	v_mfma_f32_16x16x32_bf16 v[60:63], v[60:63], v[204:207], 0
	v_fma_f32 v44, v84, v44, v52
	v_fma_f32 v45, v85, v45, v53
	v_and_b32_e32 v77, 0xffff0000, v21
	v_lshlrev_b32_e32 v84, 16, v21
	v_and_b32_e32 v53, 0xffff0000, v17
	v_lshlrev_b32_e32 v52, 16, v17
	v_cndmask_b32_e32 v85, 0, v77, vcc
	v_cndmask_b32_e32 v84, 0, v84, vcc
	v_pk_add_f32 v[84:85], v[84:85], v[52:53] neg_lo:[0,1] neg_hi:[0,1]
	v_and_b32_e32 v95, 0xffff0000, v19
	v_pk_fma_f32 v[84:85], v[84:85], v[54:55], v[52:53]
	s_waitcnt vmcnt(0) lgkmcnt(0)
	s_nop 1
	v_mfma_f32_16x16x32_bf16 v[52:55], v[78:81], v[208:211], v[60:63]
	s_nop 7
	ds_write_b32 v108, v52 offset:192
	ds_write_b32 v108, v53 offset:452
	ds_write_b32 v108, v54 offset:712
	ds_write_b32 v108, v55 offset:972
	s_waitcnt lgkmcnt(0)
	s_barrier
	s_cmp_lg_u32 s101, 0
	s_cbranch_scc1 .Lres_skip_355
	v_readlane_b32 s98, v241, 51
	v_readlane_b32 s99, v241, 52
	global_load_dwordx4 v[212:215], v147, s[42:43]
	global_load_dwordx4 v[216:219], v147, s[46:47]
	global_load_dwordx4 v[220:223], v147, s[42:43] offset:16
	global_load_dwordx4 v[224:227], v147, s[50:51]
	global_load_dwordx4 v[228:231], v147, s[72:73]
	global_load_dwordx4 v[232:235], v147, s[46:47] offset:16
	global_load_dwordx4 v[236:239], v147, s[50:51] offset:16
	global_load_dwordx4 v[244:247], v147, s[72:73] offset:16
	global_load_dwordx4 v[248:251], v147, s[98:99]
	global_load_dwordx4 v[252:255], v147, s[98:99] offset:16
.Lres_skip_355:
	v_and_b32_e32 v56, 0xffff0000, v23
	v_lshlrev_b32_e32 v58, 16, v23
	v_lshlrev_b32_e32 v94, 16, v19
	v_cndmask_b32_e32 v57, 0, v56, vcc
	v_cndmask_b32_e32 v56, 0, v58, vcc
	v_pk_add_f32 v[96:97], v[56:57], v[94:95] neg_lo:[0,1] neg_hi:[0,1]
	v_and_b32_e32 v56, 0xffff0000, v7
	v_lshlrev_b32_e32 v58, 16, v7
	v_and_b32_e32 v61, 0xffff0000, v3
	v_lshlrev_b32_e32 v60, 16, v3
	v_cndmask_b32_e32 v57, 0, v56, vcc
	v_cndmask_b32_e32 v56, 0, v58, vcc
	v_pk_add_f32 v[62:63], v[56:57], v[60:61] neg_lo:[0,1] neg_hi:[0,1]
	v_pk_fma_f32 v[88:89], v[62:63], v[50:51], v[60:61]
	v_and_b32_e32 v60, 0xffff0000, v15
	v_lshlrev_b32_e32 v62, 16, v15
	v_and_b32_e32 v51, 0xffff0000, v11
	v_lshlrev_b32_e32 v50, 16, v11
	v_cndmask_b32_e32 v61, 0, v60, vcc
	v_cndmask_b32_e32 v60, 0, v62, vcc
	v_pk_add_f32 v[60:61], v[60:61], v[50:51] neg_lo:[0,1] neg_hi:[0,1]
	v_lshlrev_b32_e32 v62, 16, v6
	v_pk_fma_f32 v[100:101], v[60:61], v[74:75], v[50:51]
	v_and_b32_e32 v60, 0xffff0000, v6
	v_and_b32_e32 v51, 0xffff0000, v2
	v_lshlrev_b32_e32 v50, 16, v2
	v_cndmask_b32_e32 v61, 0, v60, vcc
	v_cndmask_b32_e32 v60, 0, v62, vcc
	v_pk_add_f32 v[60:61], v[60:61], v[50:51] neg_lo:[0,1] neg_hi:[0,1]
	v_and_b32_e32 v75, 0xffff0000, v10
	v_pk_fma_f32 v[86:87], v[60:61], v[48:49], v[50:51]
	v_and_b32_e32 v48, 0xffff0000, v14
	v_lshlrev_b32_e32 v50, 16, v14
	v_lshlrev_b32_e32 v74, 16, v10
	v_cndmask_b32_e32 v49, 0, v48, vcc
	v_cndmask_b32_e32 v48, 0, v50, vcc
	v_pk_add_f32 v[78:79], v[48:49], v[74:75] neg_lo:[0,1] neg_hi:[0,1]
	v_pk_fma_f32 v[102:103], v[78:79], v[72:73], v[74:75]
	v_and_b32_e32 v74, 0xffff0000, v5
	v_lshlrev_b32_e32 v77, 16, v5
	v_and_b32_e32 v73, 0xffff0000, v1
	v_lshlrev_b32_e32 v72, 16, v1
	v_cndmask_b32_e32 v75, 0, v74, vcc
	v_cndmask_b32_e32 v74, 0, v77, vcc
	v_pk_add_f32 v[74:75], v[74:75], v[72:73] neg_lo:[0,1] neg_hi:[0,1]
	ds_read2_b32 v[80:81], v76 offset1:1
	v_pk_fma_f32 v[92:93], v[66:67], v[74:75], v[72:73]
	v_and_b32_e32 v72, 0xffff0000, v13
	v_lshlrev_b32_e32 v74, 16, v13
	v_and_b32_e32 v67, 0xffff0000, v9
	v_lshlrev_b32_e32 v66, 16, v9
	v_cndmask_b32_e32 v73, 0, v72, vcc
	v_cndmask_b32_e32 v72, 0, v74, vcc
	v_pk_add_f32 v[72:73], v[72:73], v[66:67] neg_lo:[0,1] neg_hi:[0,1]
	v_lshlrev_b32_e32 v74, 16, v12
	v_pk_fma_f32 v[104:105], v[72:73], v[70:71], v[66:67]
	v_and_b32_e32 v70, 0xffff0000, v4
	v_lshlrev_b32_e32 v72, 16, v4
	v_and_b32_e32 v67, 0xffff0000, v0
	v_lshlrev_b32_e32 v66, 16, v0
	v_cndmask_b32_e32 v71, 0, v70, vcc
	v_cndmask_b32_e32 v70, 0, v72, vcc
	v_pk_add_f32 v[70:71], v[70:71], v[66:67] neg_lo:[0,1] neg_hi:[0,1]
	v_and_b32_e32 v72, 0xffff0000, v12
	v_pk_fma_f32 v[90:91], v[64:65], v[70:71], v[66:67]
	v_and_b32_e32 v71, 0xffff0000, v8
	v_lshlrev_b32_e32 v70, 16, v8
	v_cndmask_b32_e32 v73, 0, v72, vcc
	v_cndmask_b32_e32 v72, 0, v74, vcc
	v_pk_add_f32 v[72:73], v[72:73], v[70:71] neg_lo:[0,1] neg_hi:[0,1]
	v_add_u32_e32 v99, 0x4100, v76
	v_pk_fma_f32 v[106:107], v[72:73], v[68:69], v[70:71]
	v_add_u32_e32 v83, 0x4108, v76
	v_add_u32_e32 v98, 0x4110, v76
	v_add_u32_e32 v82, 0x4118, v76
	ds_read2_b32 v[108:109], v76 offset0:2 offset1:3
	ds_read2_b32 v[110:111], v76 offset0:4 offset1:5
	ds_read2_b32 v[112:113], v76 offset0:6 offset1:7
	s_waitcnt vmcnt(0) lgkmcnt(3)
	v_mov_b32_e32 v52, v212
	v_mov_b32_e32 v53, v213
	v_mov_b32_e32 v54, v214
	v_add_f32_e32 v52, v52, v80
	v_mul_f32_e64 v68, |v52|, s91
	v_exp_f32_e32 v80, v68
	ds_read2_b32 v[150:151], v99 offset1:1
	ds_read2_b32 v[118:119], v83 offset1:1
	ds_read2_b32 v[116:117], v98 offset1:1
	ds_read2_b32 v[114:115], v82 offset1:1
	v_add_f32_e32 v80, 1.0, v80
	v_cmp_gt_f32_e32 vcc, s3, v80
	s_and_b32 s0, s0, 0xfffff000
	s_or_b32 s4, s4, s0
	v_cndmask_b32_e64 v99, 0, 32, vcc
	v_ldexp_f32 v80, v80, v99
	v_log_f32_e32 v80, v80
	v_max_f32_e64 v52, -v52, 0
	s_waitcnt vmcnt(0) lgkmcnt(3)
	v_mov_b32_e32 v56, v216
	v_mov_b32_e32 v57, v217
	v_add_f32_e32 v56, v56, v150
	v_mul_f32_e32 v56, 0xbfb8aa3b, v56
	v_mul_f32_e32 v82, 0x3f317217, v80
	v_fma_f32 v82, v80, s10, -v82
	v_fmac_f32_e32 v82, 0x3377d1cf, v80
	v_fmac_f32_e32 v82, 0x3f317217, v80
	v_cmp_lt_f32_e64 s[0:1], |v80|, s11
	v_add_f32_e32 v53, v53, v81
	v_exp_f32_e32 v56, v56
	v_cndmask_b32_e64 v80, v80, v82, s[0:1]
	v_cndmask_b32_e32 v82, 0, v128, vcc
	v_sub_f32_e32 v80, v80, v82
	v_add_f32_e32 v52, v52, v80
	v_mul_f32_e64 v80, |v53|, s91
	v_exp_f32_e32 v80, v80
	v_sub_f32_e32 v52, -0.5, v52
	v_mul_f32_e32 v52, 0x3fb8aa3b, v52
	v_exp_f32_e32 v98, v52
	v_add_f32_e32 v52, 1.0, v56
	v_rcp_f32_e32 v56, v52
	v_add_f32_e32 v52, 1.0, v80
	v_cmp_gt_f32_e32 vcc, s3, v52
	v_add_f32_e32 v57, v57, v151
	v_max_f32_e64 v53, -v53, 0
	v_cndmask_b32_e64 v80, 0, 32, vcc
	v_ldexp_f32 v52, v52, v80
	v_log_f32_e32 v52, v52
	s_waitcnt vmcnt(0)
	v_mov_b32_e32 v48, v220
	v_mov_b32_e32 v49, v221
	v_mov_b32_e32 v50, v222
	v_mov_b32_e32 v51, v223
	v_mul_f32_e32 v149, v106, v224
	v_add_f32_e32 v54, v54, v108
	v_mul_f32_e32 v150, v107, v225
	v_mul_f32_e32 v60, 0x3f317217, v52
	v_fma_f32 v60, v52, s10, -v60
	v_fmac_f32_e32 v60, 0x3377d1cf, v52
	v_fmac_f32_e32 v60, 0x3f317217, v52
	v_cmp_lt_f32_e64 s[0:1], |v52|, s11
	v_add_f32_e32 v48, v48, v110
	v_add_f32_e32 v49, v49, v111
	v_cndmask_b32_e64 v52, v52, v60, s[0:1]
	v_cndmask_b32_e32 v60, 0, v128, vcc
	v_sub_f32_e32 v52, v52, v60
	v_add_f32_e32 v52, v53, v52
	v_mul_f32_e32 v53, 0xbfb8aa3b, v57
	v_exp_f32_e32 v53, v53
	v_sub_f32_e32 v52, -0.5, v52
	v_mul_f32_e32 v52, 0x3fb8aa3b, v52
	v_exp_f32_e32 v99, v52
	v_add_f32_e32 v52, 1.0, v53
	v_rcp_f32_e32 v57, v52
	v_mul_f32_e64 v52, |v54|, s91
	v_exp_f32_e32 v60, v52
	v_readlane_b32 s74, v241, 51
	v_pk_add_f32 v[52:53], v[56:57], -1.0 op_sel_hi:[1,0]
	v_readlane_b32 s75, v241, 52
	v_add_f32_e32 v60, 1.0, v60
	v_cmp_gt_f32_e32 vcc, s3, v60
	s_waitcnt vmcnt(0)
	v_pk_fma_f32 v[52:53], v[228:229], v[52:53], 1.0 op_sel_hi:[1,1,0]
	v_add_f32_e32 v50, v50, v112
	v_cndmask_b32_e64 v61, 0, 32, vcc
	v_ldexp_f32 v60, v60, v61
	v_log_f32_e32 v64, v60
	v_pk_mul_f32 v[60:61], v[106:107], v[52:53]
	v_max_f32_e64 v53, -v54, 0
	s_waitcnt lgkmcnt(2)
	v_add_f32_e32 v52, v218, v118
	v_mul_f32_e32 v54, 0x3f317217, v64
	v_fma_f32 v54, v64, s10, -v54
	v_fmac_f32_e32 v54, 0x3377d1cf, v64
	v_fmac_f32_e32 v54, 0x3f317217, v64
	v_cmp_lt_f32_e64 s[0:1], |v64|, s11
	v_cndmask_b32_e32 v58, 0, v128, vcc
	v_mul_f32_e32 v52, 0xbfb8aa3b, v52
	v_cndmask_b32_e64 v54, v64, v54, s[0:1]
	v_sub_f32_e32 v54, v54, v58
	v_add_f32_e32 v53, v53, v54
	v_sub_f32_e32 v53, -0.5, v53
	v_mul_f32_e32 v53, 0x3fb8aa3b, v53
	v_exp_f32_e32 v58, v53
	v_add_f32_e32 v53, v215, v109
	v_exp_f32_e32 v52, v52
	v_mul_f32_e64 v54, |v53|, s91
	v_exp_f32_e32 v54, v54
	v_max_f32_e64 v53, -v53, 0
	v_add_f32_e32 v52, 1.0, v52
	v_rcp_f32_e32 v64, v52
	v_add_f32_e32 v52, 1.0, v54
	v_cmp_gt_f32_e32 vcc, s3, v52
	v_mul_f32_e32 v106, v104, v226
	v_mul_f32_e32 v107, v105, v227
	v_cndmask_b32_e64 v54, 0, 32, vcc
	v_ldexp_f32 v52, v52, v54
	v_log_f32_e32 v52, v52
	v_add_f32_e32 v54, v219, v119
	v_add_f32_e32 v51, v51, v113
	v_mul_f32_e32 v55, 0x3f317217, v52
	v_fma_f32 v55, v52, s10, -v55
	v_fmac_f32_e32 v55, 0x3377d1cf, v52
	v_fmac_f32_e32 v55, 0x3f317217, v52
	v_cmp_lt_f32_e64 s[0:1], |v52|, s11
	v_mul_f32_e32 v151, v150, v150
	v_fmac_f32_e32 v151, v149, v149
	v_cndmask_b32_e64 v52, v52, v55, s[0:1]
	v_cndmask_b32_e32 v55, 0, v128, vcc
	v_sub_f32_e32 v52, v52, v55
	v_add_f32_e32 v52, v53, v52
	v_mul_f32_e32 v53, 0xbfb8aa3b, v54
	v_exp_f32_e32 v53, v53
	v_sub_f32_e32 v52, -0.5, v52
	v_mul_f32_e32 v52, 0x3fb8aa3b, v52
	v_exp_f32_e32 v59, v52
	v_add_f32_e32 v52, 1.0, v53
	v_rcp_f32_e32 v65, v52
	v_mul_f32_e64 v52, |v48|, s91
	v_exp_f32_e32 v54, v52
	v_max_f32_e64 v48, -v48, 0
	v_pk_add_f32 v[52:53], v[64:65], -1.0 op_sel_hi:[1,0]
	v_fmac_f32_e32 v151, v106, v106
	v_add_f32_e32 v54, 1.0, v54
	v_cmp_gt_f32_e32 vcc, s3, v54
	v_pk_fma_f32 v[52:53], v[230:231], v[52:53], 1.0 op_sel_hi:[1,1,0]
	v_fmac_f32_e32 v151, v107, v107
	v_cndmask_b32_e64 v55, 0, 32, vcc
	v_ldexp_f32 v54, v54, v55
	v_log_f32_e32 v54, v54
	v_pk_mul_f32 v[62:63], v[104:105], v[52:53]
	s_waitcnt vmcnt(0) lgkmcnt(1)
	v_add_f32_e32 v52, v232, v116
	v_mul_f32_e32 v52, 0xbfb8aa3b, v52
	v_mul_f32_e32 v53, 0x3f317217, v54
	v_fma_f32 v53, v54, s10, -v53
	v_fmac_f32_e32 v53, 0x3377d1cf, v54
	v_fmac_f32_e32 v53, 0x3f317217, v54
	v_cmp_lt_f32_e64 s[0:1], |v54|, s11
	v_exp_f32_e32 v52, v52
	s_waitcnt vmcnt(0)
	v_mul_f32_e32 v76, v102, v236
	v_cndmask_b32_e64 v53, v54, v53, s[0:1]
	v_cndmask_b32_e32 v54, 0, v128, vcc
	v_sub_f32_e32 v53, v53, v54
	v_add_f32_e32 v48, v48, v53
	v_mul_f32_e64 v53, |v49|, s91
	v_exp_f32_e32 v53, v53
	v_add_f32_e32 v52, 1.0, v52
	v_rcp_f32_e32 v66, v52
	v_max_f32_e64 v49, -v49, 0
	v_add_f32_e32 v52, 1.0, v53
	v_cmp_gt_f32_e32 vcc, s3, v52
	v_mul_f32_e64 v72, |v50|, s91
	v_exp_f32_e32 v104, v72
	v_cndmask_b32_e64 v53, 0, 32, vcc
	v_ldexp_f32 v52, v52, v53
	v_log_f32_e32 v52, v52
	v_add_f32_e32 v53, v233, v117
	v_mul_f32_e32 v77, v103, v237
	v_max_f32_e64 v50, -v50, 0
	v_mul_f32_e32 v54, 0x3f317217, v52
	v_fma_f32 v54, v52, s10, -v54
	v_fmac_f32_e32 v54, 0x3377d1cf, v52
	v_fmac_f32_e32 v54, 0x3f317217, v52
	v_cmp_lt_f32_e64 s[0:1], |v52|, s11
	v_fmac_f32_e32 v151, v76, v76
	v_fmac_f32_e32 v151, v77, v77
	v_cndmask_b32_e64 v52, v52, v54, s[0:1]
	v_cndmask_b32_e32 v54, 0, v128, vcc
	v_sub_f32_e32 v52, v52, v54
	v_add_f32_e32 v49, v49, v52
	v_mul_f32_e32 v52, 0xbfb8aa3b, v53
	v_exp_f32_e32 v67, v52
	v_pk_fma_f32 v[46:47], v[96:97], v[46:47], v[94:95]
	v_sub_f32_e32 v48, -0.5, v48
	v_add_f32_e32 v67, 1.0, v67
	v_rcp_f32_e32 v67, v67
	v_sub_f32_e32 v49, -0.5, v49
	v_mul_f32_e32 v48, 0x3fb8aa3b, v48
	v_mul_f32_e32 v49, 0x3fb8aa3b, v49
	v_pk_add_f32 v[72:73], v[66:67], -1.0 op_sel_hi:[1,0]
	v_exp_f32_e32 v48, v48
	s_waitcnt vmcnt(0)
	v_mov_b32_e32 v68, v244
	v_mov_b32_e32 v69, v245
	v_mov_b32_e32 v70, v246
	v_mov_b32_e32 v71, v247
	v_pk_fma_f32 v[68:69], v[68:69], v[72:73], 1.0 op_sel_hi:[1,1,0]
	v_add_f32_e32 v72, 1.0, v104
	v_cmp_gt_f32_e32 vcc, s3, v72
	v_pk_mul_f32 v[68:69], v[102:103], v[68:69]
	v_exp_f32_e32 v49, v49
	v_cndmask_b32_e64 v73, 0, 32, vcc
	v_ldexp_f32 v72, v72, v73
	v_log_f32_e32 v72, v72
	s_waitcnt lgkmcnt(0)
	v_add_f32_e32 v73, v234, v114
	v_and_b32_e32 v140, 63, v137
	v_readlane_b32 s37, v241, 34
	v_mul_f32_e32 v78, 0x3f317217, v72
	v_fma_f32 v78, v72, s10, -v78
	v_fmac_f32_e32 v78, 0x3377d1cf, v72
	v_fmac_f32_e32 v78, 0x3f317217, v72
	v_cmp_lt_f32_e64 s[0:1], |v72|, s11
	v_readlane_b32 s38, v241, 35
	v_readlane_b32 s39, v241, 36
	v_cndmask_b32_e64 v72, v72, v78, s[0:1]
	v_cndmask_b32_e32 v78, 0, v128, vcc
	v_sub_f32_e32 v72, v72, v78
	v_add_f32_e32 v50, v50, v72
	v_mul_f32_e32 v72, 0xbfb8aa3b, v73
	v_mul_f32_e64 v73, |v51|, s91
	v_exp_f32_e32 v73, v73
	v_mul_f32_e32 v78, v100, v238
	v_exp_f32_e32 v72, v72
	v_max_f32_e64 v51, -v51, 0
	v_add_f32_e32 v73, 1.0, v73
	v_cmp_gt_f32_e32 vcc, s3, v73
	v_add_f32_e32 v72, 1.0, v72
	v_rcp_f32_e32 v72, v72
	v_cndmask_b32_e64 v74, 0, 32, vcc
	v_ldexp_f32 v73, v73, v74
	v_log_f32_e32 v73, v73
	v_add_f32_e32 v74, v235, v115
	v_mul_f32_e32 v74, 0xbfb8aa3b, v74
	v_exp_f32_e32 v74, v74
	v_mul_f32_e32 v79, 0x3f317217, v73
	v_fma_f32 v79, v73, s10, -v79
	v_fmac_f32_e32 v79, 0x3377d1cf, v73
	v_fmac_f32_e32 v79, 0x3f317217, v73
	v_cmp_lt_f32_e64 s[0:1], |v73|, s11
	v_fmac_f32_e32 v151, v78, v78
	v_sub_f32_e32 v50, -0.5, v50
	v_cndmask_b32_e64 v73, v73, v79, s[0:1]
	v_cndmask_b32_e32 v79, 0, v128, vcc
	v_sub_f32_e32 v73, v73, v79
	v_add_f32_e32 v51, v51, v73
	v_add_f32_e32 v73, 1.0, v74
	v_rcp_f32_e32 v73, v73
	v_mul_f32_e32 v79, v101, v239
	v_cmp_lt_i32_e32 vcc, v130, v131
	v_fmac_f32_e32 v151, v79, v79
	v_pk_add_f32 v[74:75], v[72:73], -1.0 op_sel_hi:[1,0]
	v_sub_f32_e32 v51, -0.5, v51
	v_pk_fma_f32 v[70:71], v[70:71], v[74:75], 1.0 op_sel_hi:[1,1,0]
	v_cndmask_b32_e32 v74, v129, v130, vcc
	v_pk_mul_f32 v[70:71], v[100:101], v[70:71]
	v_lshlrev_b32_e32 v100, 2, v74
	v_pk_mul_f32 v[74:75], v[90:91], v[60:61]
	v_cmp_lt_i32_e32 vcc, v132, v131
	s_waitcnt vmcnt(0)
	v_pk_mul_f32 v[74:75], v[74:75], v[248:249]
	v_mul_f32_e32 v50, 0x3fb8aa3b, v50
	v_add_f32_e32 v74, 0, v74
	v_add_f32_e32 v80, v74, v75
	v_pk_mul_f32 v[74:75], v[92:93], v[62:63]
	v_mul_f32_e32 v51, 0x3fb8aa3b, v51
	v_pk_mul_f32 v[74:75], v[74:75], v[250:251]
	v_mov_b32_e32 v81, v43
	v_add_f32_e32 v74, v80, v74
	v_add_f32_e32 v80, v74, v75
	v_pk_mul_f32 v[74:75], v[86:87], v[68:69]
	v_exp_f32_e32 v50, v50
	s_waitcnt vmcnt(0)
	v_mov_b32_e32 v52, v252
	v_mov_b32_e32 v53, v253
	v_pk_mul_f32 v[52:53], v[74:75], v[52:53]
	v_exp_f32_e32 v51, v51
	v_add_f32_e32 v52, v80, v52
	v_add_f32_e32 v74, v52, v53
	v_pk_mul_f32 v[52:53], v[88:89], v[70:71]
	v_lshlrev_b32_e32 v80, 1, v146
	v_pk_mul_f32 v[52:53], v[52:53], v[254:255]
	v_cndmask_b32_e32 v54, v129, v132, vcc
	v_add_f32_e32 v52, v74, v52
	v_add_f32_e32 v52, v52, v53
	ds_bpermute_b32 v53, v100, v52
	v_lshlrev_b32_e32 v54, 2, v54
	v_cmp_lt_i32_e32 vcc, v133, v131
	ds_bpermute_b32 v55, v100, v151
	s_movk_i32 s0, 0x820
	s_waitcnt lgkmcnt(1)
	v_add_f32_e32 v52, v52, v53
	ds_bpermute_b32 v53, v54, v52
	v_cndmask_b32_e32 v74, v129, v133, vcc
	v_lshlrev_b32_e32 v82, 2, v74
	s_waitcnt lgkmcnt(1)
	v_add_f32_e32 v83, v151, v55
	ds_bpermute_b32 v100, v54, v83
	s_waitcnt lgkmcnt(1)
	v_add_f32_e32 v52, v52, v53
	ds_bpermute_b32 v53, v82, v52
	v_cmp_lt_i32_e32 vcc, 0, v138
	v_readlane_b32 s44, v241, 41
	v_readlane_b32 s45, v241, 42
	v_readlane_b32 s48, v241, 45
	s_waitcnt lgkmcnt(0)
	v_add_f32_e32 v74, v52, v53
	v_pk_mul_f32 v[52:53], v[40:41], v[74:75] op_sel_hi:[1,0]
	v_pk_mul_f32 v[54:55], v[84:85], v[74:75] op_sel_hi:[1,0]
	v_cvt_pk_bf16_f32 v52, v52, v53
	v_cvt_pk_bf16_f32 v53, v54, v55
	v_pk_mul_f32 v[54:55], v[44:45], v[74:75] op_sel_hi:[1,0]
	v_pk_mul_f32 v[74:75], v[46:47], v[74:75] op_sel_hi:[1,0]
	v_cvt_pk_bf16_f32 v54, v54, v55
	v_cvt_pk_bf16_f32 v55, v74, v75
	v_add_u32_e32 v74, s4, v141
	v_ashrrev_i32_e32 v75, 31, v74
	v_lshlrev_b64 v[74:75], 10, v[74:75]
	v_lshl_add_u64 v[74:75], s[52:53], 0, v[74:75]
	v_lshl_add_u64 v[74:75], v[74:75], 0, v[80:81]
	global_store_dwordx4 v[74:75], v[52:55], off nt
	s_waitcnt lgkmcnt(0)
	s_barrier
	v_readlane_b32 s49, v241, 46
	v_add3_u32 v54, s94, v148, v144
	v_pk_add_f32 v[52:53], v[98:99], 0 neg_lo:[1,1] neg_hi:[1,1]
	ds_write2_b32 v54, v52, v53 offset1:1
	v_pk_add_f32 v[52:53], v[58:59], 0 neg_lo:[1,1] neg_hi:[1,1]
	ds_write2_b32 v54, v52, v53 offset0:2 offset1:3
	v_pk_add_f32 v[52:53], v[48:49], 0 neg_lo:[1,1] neg_hi:[1,1]
	ds_write2_b32 v54, v52, v53 offset0:4 offset1:5
	v_pk_add_f32 v[52:53], v[50:51], 0 neg_lo:[1,1] neg_hi:[1,1]
	ds_write2_b32 v54, v52, v53 offset0:6 offset1:7
	v_lshl_add_u32 v52, v140, 2, s94
	v_mul_lo_u32 v53, v138, s0
	s_waitcnt lgkmcnt(0)
	s_barrier
	v_add_u32_e32 v53, v52, v53
	ds_read2_b32 v[74:75], v53 offset1:65
	v_add_f32_e32 v55, v83, v100
	ds_bpermute_b32 v80, v82, v55
	ds_read2_b32 v[82:83], v53 offset0:130 offset1:195
	v_readlane_b32 s76, v241, 53
	s_waitcnt lgkmcnt(2)
	v_add_f32_e32 v52, 0, v74
	v_add_f32_e32 v81, v52, v75
	ds_write2_b32 v53, v52, v81 offset1:65
	v_add_u32_e32 v52, 0x400, v53
	ds_read2_b32 v[74:75], v52 offset0:4 offset1:69
	s_waitcnt lgkmcnt(2)
	v_add_f32_e32 v81, v81, v82
	v_add_f32_e32 v94, v81, v83
	ds_read2_b32 v[82:83], v52 offset0:134 offset1:199
	ds_write2_b32 v53, v81, v94 offset0:130 offset1:195
	s_waitcnt lgkmcnt(2)
	v_add_f32_e32 v74, v94, v74
	v_add_f32_e32 v75, v74, v75
	ds_write2_b32 v52, v74, v75 offset0:4 offset1:69
	s_waitcnt lgkmcnt(2)
	v_add_f32_e32 v74, v75, v82
	v_add_f32_e32 v75, v74, v83
	ds_write2_b32 v52, v74, v75 offset0:134 offset1:199
	v_lshl_add_u32 v74, v137, 2, 0
	v_add_u32_e32 v74, 0x24000, v74
	ds_write_b32 v74, v75
	s_waitcnt lgkmcnt(0)
	s_barrier
	v_mov_b32_e32 v81, 0
	v_readlane_b32 s77, v241, 54
	v_readlane_b32 s78, v241, 55
	v_readlane_b32 s79, v241, 56
	v_readlane_b32 s80, v241, 57
	v_readlane_b32 s81, v241, 58
	v_readlane_b32 s82, v241, 59
	v_readlane_b32 s83, v241, 60
	v_readlane_b32 s84, v241, 61
	v_readlane_b32 s85, v241, 62
	v_readlane_b32 s86, v241, 63
	v_readlane_b32 s87, v240, 0
	s_and_saveexec_b64 s[0:1], vcc
	s_cbranch_execz .LBB0_783
	v_cmp_lt_u32_e32 vcc, 7, v138
	v_mov_b32_e32 v81, 0
	v_mov_b32_e32 v74, 0
	s_and_saveexec_b64 s[4:5], vcc
	s_cbranch_execz .LBB0_778
	s_add_i32 s6, 0, 0x24000
	v_and_b32_e32 v74, 0x7ffffff8, v138
	v_lshl_add_u32 v75, v140, 2, s6
	s_mov_b32 s12, 0
	v_mov_b32_e32 v81, 0
	s_mov_b64 s[6:7], 0

.LBB0_1024:
	s_or_b64 exec, exec, s[30:31]
	s_add_i32 s76, s76, 1
	s_bitcmp1_b32 s76, 0
	s_cselect_b32 s30, 0x11400, 0
	s_add_i32 s77, s30, 0
	v_add3_u32 v52, s77, v97, v72
	s_cmp_lg_u64 s[0:1], 0
	s_cbranch_scc1 .Lscan_w0_stage
	s_waitcnt vmcnt(5)
	ds_write_b128 v52, v[12:15]
	s_waitcnt vmcnt(4)
	ds_write_b128 v52, v[16:19] offset:11776
	s_waitcnt vmcnt(3)
	ds_write_b128 v52, v[20:23] offset:23552
	s_waitcnt vmcnt(2)
	ds_write_b128 v52, v[24:27] offset:35328
	s_waitcnt vmcnt(1)
	ds_write_b128 v52, v[28:31] offset:47104
	s_waitcnt vmcnt(0)
	ds_write_b128 v52, v[32:35] offset:58880
	s_branch .Lscan_stage_done
.Lscan_w0_stage:
	s_waitcnt vmcnt(24)
	ds_write_b128 v52, v[12:15]
	ds_write_b128 v52, v[16:19] offset:11776
	ds_write_b128 v52, v[20:23] offset:23552
	ds_write_b128 v52, v[24:27] offset:35328
	ds_write_b128 v52, v[28:31] offset:47104
	ds_write_b128 v52, v[32:35] offset:58880
.Lscan_stage_done:
	s_and_saveexec_b64 s[30:31], s[4:5]
	s_cbranch_execz .LBB0_1027
	v_add_u32_e32 v12, s77, v99
	v_add3_u32 v12, v12, v100, v72
	ds_write_b128 v12, v[0:3] offset:9216
	s_or_b64 exec, exec, s[30:31]
	s_and_saveexec_b64 s[30:31], s[6:7]
	s_cbranch_execnz .LBB0_1028
